# phase 0 modulation GEMV: 16 rows in flight per trip; prep_ew l2norm sums via DPP
# speedup vs baseline: 1.0505x; 1.0116x over previous
; DI unsigned pk2(float lo, float hi) { f32x2_t v; v[0] = lo; v[1] = hi; bf16x2_t b = __builtin_convertvector(v, bf16x2_t); return __builtin_bit_cast(unsigned, b); }
; DI float bflo(unsigned u) { return __uint_as_float(u << 16); }
; DI float bfhi(unsigned u) { return __uint_as_float(u & 0xffff0000u); }
; DI float siluf_(float x) { return x / (1.f + __expf(-x)); }
; DI void prep_ew_item(const Params& p, int l, int item, bf16_t* lds) {
;     ...
;       for (int i = 0; i < 4; ++i) {
;         const int ts = tl - 3 + i;
;         if (ts >= 0) {
;           u32x4 v = *(const u32x4*)(RC + (size_t)ts * 1536 + ch); unsigned w[4] = {v.x, v.y, v.z, v.w};
;           const float* cw = p.convw + ((size_t)l * 4 + i) * 1536 + ch;
;           f32x4 c0 = *(const f32x4*)cw, c1 = *(const f32x4*)(cw + 4);
;           a[0] += bflo(w[0]) * c0[0]; a[1] += bfhi(w[0]) * c0[1]; a[2] += bflo(w[1]) * c0[2]; a[3] += bfhi(w[1]) * c0[3];
;           a[4] += bflo(w[2]) * c1[0]; a[5] += bfhi(w[2]) * c1[1]; a[6] += bflo(w[3]) * c1[2]; a[7] += bfhi(w[3]) * c1[3];
;         }
;     ...
;       float ss = 0.f;
; #pragma unroll
;       for (int j = 0; j < 8; ++j) { a[j] = siluf_(a[j]); ss += a[j] * a[j]; }
;       float mul = 1.f;
;       if (part < 2) {
;         ss += __shfl_xor(ss, 1); ss += __shfl_xor(ss, 2); ss += __shfl_xor(ss, 4); ss += __shfl_xor(ss, 8);
;         mul = rsqrtf(ss + EPS) * (part == 0 ? 0.08838834764831845f : 1.f);
;       }
;       u32x4 o; o.x = pk2(a[0] * mul, a[1] * mul); o.y = pk2(a[2] * mul, a[3] * mul); o.z = pk2(a[4] * mul, a[5] * mul); o.w = pk2(a[6] * mul, a[7] * mul);
;       *(u32x4*)(CQ + (size_t)t * 1536 + ch) = o;
.LBB0_856:
	s_or_b64 exec, exec, s[26:27]
	v_mul_f32_e32 v52, 0xbfb8aa3b, v44
	v_exp_f32_e32 v54, v52
	v_mul_f32_e32 v52, 0xbfb8aa3b, v45
	v_exp_f32_e32 v55, v52
	v_mul_f32_e32 v52, 0xbfb8aa3b, v46
	v_exp_f32_e32 v64, v52
	v_mul_f32_e32 v52, 0xbfb8aa3b, v47
	v_exp_f32_e32 v65, v52
	v_mul_f32_e32 v52, 0xbfb8aa3b, v48
	v_mul_f32_e32 v53, 0xbfb8aa3b, v49
	v_exp_f32_e32 v52, v52
	v_exp_f32_e32 v53, v53
	v_pk_add_f32 v[64:65], v[64:65], 1.0 op_sel_hi:[1,0]
	v_pk_add_f32 v[54:55], v[54:55], 1.0 op_sel_hi:[1,0]
	v_mul_f32_e32 v50, 0xbfb8aa3b, v42
	v_pk_add_f32 v[52:53], v[52:53], 1.0 op_sel_hi:[1,0]
	v_mul_f32_e32 v51, 0xbfb8aa3b, v43
	v_div_scale_f32 v66, s[6:7], v53, v53, v49
	v_rcp_f32_e32 v67, v66
	v_exp_f32_e32 v50, v50
	v_exp_f32_e32 v51, v51
	v_fma_f32 v68, -v66, v67, 1.0
	v_fmac_f32_e32 v67, v68, v67
	v_div_scale_f32 v68, vcc, v49, v53, v49
	v_mul_f32_e32 v69, v68, v67
	s_waitcnt vmcnt(6)
	v_fma_f32 v70, -v66, v69, v68
	v_fmac_f32_e32 v69, v70, v67
	v_fma_f32 v66, -v66, v69, v68
	v_div_fmas_f32 v66, v66, v67, v69
	v_div_fixup_f32 v49, v66, v53, v49
	v_div_scale_f32 v53, s[6:7], v52, v52, v48
	v_rcp_f32_e32 v66, v53
	v_pk_add_f32 v[50:51], v[50:51], 1.0 op_sel_hi:[1,0]
	v_fma_f32 v67, -v53, v66, 1.0
	v_fmac_f32_e32 v66, v67, v66
	v_div_scale_f32 v67, vcc, v48, v52, v48
	v_mul_f32_e32 v68, v67, v66
	v_fma_f32 v69, -v53, v68, v67
	v_fmac_f32_e32 v68, v69, v66
	v_fma_f32 v53, -v53, v68, v67
	v_div_fmas_f32 v53, v53, v66, v68
	v_div_scale_f32 v66, s[6:7], v65, v65, v47
	v_rcp_f32_e32 v67, v66
	v_div_fixup_f32 v48, v53, v52, v48
	v_pk_mul_f32 v[52:53], v[48:49], v[48:49]
	v_fma_f32 v68, -v66, v67, 1.0
	v_fmac_f32_e32 v67, v68, v67
	v_div_scale_f32 v68, vcc, v47, v65, v47
	v_mul_f32_e32 v69, v68, v67
	v_fma_f32 v70, -v66, v69, v68
	v_fmac_f32_e32 v69, v70, v67
	v_fma_f32 v66, -v66, v69, v68
	v_div_fmas_f32 v66, v66, v67, v69
	v_div_fixup_f32 v47, v66, v65, v47
	v_div_scale_f32 v65, s[6:7], v64, v64, v46
	v_rcp_f32_e32 v66, v65
	s_nop 0
	v_fma_f32 v67, -v65, v66, 1.0
	v_fmac_f32_e32 v66, v67, v66
	v_div_scale_f32 v67, vcc, v46, v64, v46
	v_mul_f32_e32 v68, v67, v66
	v_fma_f32 v69, -v65, v68, v67
	v_fmac_f32_e32 v68, v69, v66
	v_fma_f32 v65, -v65, v68, v67
	v_div_fmas_f32 v65, v65, v66, v68
	v_div_scale_f32 v66, s[6:7], v55, v55, v45
	v_rcp_f32_e32 v67, v66
	v_div_fixup_f32 v46, v65, v64, v46
	v_pk_mul_f32 v[64:65], v[46:47], v[46:47]
	v_fma_f32 v68, -v66, v67, 1.0
	v_fmac_f32_e32 v67, v68, v67
	v_div_scale_f32 v68, vcc, v45, v55, v45
	v_mul_f32_e32 v69, v68, v67
	v_fma_f32 v70, -v66, v69, v68
	v_fmac_f32_e32 v69, v70, v67
	v_fma_f32 v66, -v66, v69, v68
	v_div_fmas_f32 v66, v66, v67, v69
	v_div_fixup_f32 v55, v66, v55, v45
	v_div_scale_f32 v45, s[6:7], v54, v54, v44
	v_rcp_f32_e32 v66, v45
	s_nop 0
	v_fma_f32 v67, -v45, v66, 1.0
	v_fmac_f32_e32 v66, v67, v66
	v_div_scale_f32 v67, vcc, v44, v54, v44
	v_mul_f32_e32 v68, v67, v66
	v_fma_f32 v69, -v45, v68, v67
	v_fmac_f32_e32 v68, v69, v66
	v_fma_f32 v45, -v45, v68, v67
	v_div_fmas_f32 v45, v45, v66, v68
	v_div_scale_f32 v66, s[6:7], v51, v51, v43
	v_rcp_f32_e32 v67, v66
	v_div_fixup_f32 v54, v45, v54, v44
	v_pk_mul_f32 v[44:45], v[54:55], v[54:55]
	v_fma_f32 v68, -v66, v67, 1.0
	v_fmac_f32_e32 v67, v68, v67
	v_div_scale_f32 v68, vcc, v43, v51, v43
	v_mul_f32_e32 v69, v68, v67
	v_fma_f32 v70, -v66, v69, v68
	v_fmac_f32_e32 v69, v70, v67
	v_fma_f32 v66, -v66, v69, v68
	v_div_fmas_f32 v66, v66, v67, v69
	v_div_fixup_f32 v43, v66, v51, v43
	v_div_scale_f32 v51, s[6:7], v50, v50, v42
	v_rcp_f32_e32 v66, v51
	s_nop 0
	v_fma_f32 v67, -v51, v66, 1.0
	v_fmac_f32_e32 v66, v67, v66
	v_div_scale_f32 v67, vcc, v42, v50, v42
	v_mul_f32_e32 v68, v67, v66
	v_fma_f32 v69, -v51, v68, v67
	v_fmac_f32_e32 v68, v69, v66
	v_fma_f32 v51, -v51, v68, v67
	v_div_fmas_f32 v51, v51, v66, v68
	v_div_fixup_f32 v42, v51, v50, v42
	v_pk_mul_f32 v[50:51], v[42:43], v[42:43]
	s_nop 0
	v_add_f32_e32 v50, v50, v51
	v_add_f32_e32 v44, v44, v50
	v_add_f32_e32 v44, v45, v44
	v_add_f32_e32 v44, v64, v44
	v_add_f32_e32 v44, v65, v44
	v_add_f32_e32 v44, v52, v44
	v_add_f32_e32 v44, v53, v44
	s_nop 1
	v_add_f32_dpp v44, v44, v44 quad_perm:[1,0,3,2] row_mask:0xf bank_mask:0xf
	v_mov_b32_e32 v52, 0
	v_mov_b32_e32 v53, 0
	s_waitcnt lgkmcnt(0)
	s_nop 1
	v_add_f32_dpp v44, v44, v44 quad_perm:[2,3,0,1] row_mask:0xf bank_mask:0xf
	s_waitcnt lgkmcnt(0)
	s_nop 1
	v_add_f32_dpp v44, v44, v44 row_half_mirror row_mask:0xf bank_mask:0xf
	s_waitcnt lgkmcnt(0)
	s_nop 1
	v_add_f32_dpp v44, v44, v44 row_mirror row_mask:0xf bank_mask:0xf
	s_waitcnt lgkmcnt(0)
	v_add_f32_e32 v44, 0x358637bd, v44
	v_cmp_gt_f32_e32 vcc, s58, v44
	v_mul_f32_e32 v45, 0x4b800000, v44
	s_nop 0
	v_cndmask_b32_e32 v44, v44, v45, vcc
	v_rsq_f32_e32 v44, v44
	s_nop 0
	v_mul_f32_e32 v45, 0x45800000, v44
	v_cndmask_b32_e32 v44, v44, v45, vcc
	v_mul_f32_e32 v50, 0x3db504f3, v44
	v_pk_mul_f32 v[42:43], v[42:43], v[50:51] op_sel_hi:[1,0]
	s_nop 0
	v_cvt_pk_bf16_f32 v44, v42, v43
	v_pk_mul_f32 v[42:43], v[54:55], v[50:51] op_sel_hi:[1,0]
	s_nop 0
	v_cvt_pk_bf16_f32 v45, v42, v43
	v_pk_mul_f32 v[42:43], v[46:47], v[50:51] op_sel_hi:[1,0]
	s_nop 0
	v_cvt_pk_bf16_f32 v46, v42, v43
	v_pk_mul_f32 v[42:43], v[48:49], v[50:51] op_sel_hi:[1,0]
	v_mov_b32_e32 v48, v52
	v_cvt_pk_bf16_f32 v47, v42, v43
	v_mad_i64_i32 v[42:43], s[6:7], v40, s57, v[34:35]
	global_store_dwordx4 v[42:43], v[44:47], off
	v_mov_b32_e32 v49, v52
	v_mov_b32_e32 v50, 0
	v_mov_b32_e32 v44, 0
	v_mov_b32_e32 v45, 0
	v_mov_b32_e32 v46, 0
	v_mov_b32_e32 v47, v52
	v_mov_b32_e32 v51, 0
	s_and_saveexec_b64 s[26:27], s[42:43]
	s_cbranch_execz .LBB0_860
	v_mad_u64_u32 v[44:45], s[6:7], v57, s57, v[36:37]
	global_load_dwordx4 v[48:51], v[44:45], off
	global_load_dwordx4 v[52:55], v[8:9], off offset:2064
	s_nop 0
	global_load_dwordx4 v[44:47], v[8:9], off offset:2048
	s_waitcnt vmcnt(2)
	v_lshlrev_b32_e32 v64, 16, v48
	v_and_b32_e32 v65, 0xffff0000, v48
	v_lshlrev_b32_e32 v48, 16, v49
	v_and_b32_e32 v49, 0xffff0000, v49
	s_waitcnt vmcnt(0)
	v_pk_fma_f32 v[46:47], v[46:47], v[48:49], 0 op_sel_hi:[1,1,0]
	v_lshlrev_b32_e32 v48, 16, v50
	v_and_b32_e32 v49, 0xffff0000, v50
	v_lshlrev_b32_e32 v50, 16, v51
	v_and_b32_e32 v51, 0xffff0000, v51
	v_pk_fma_f32 v[48:49], v[52:53], v[48:49], 0 op_sel_hi:[1,1,0]
	v_pk_fma_f32 v[52:53], v[54:55], v[50:51], 0 op_sel_hi:[1,1,0]
	v_pk_fma_f32 v[44:45], v[44:45], v[64:65], 0 op_sel_hi:[1,1,0]
	v_mov_b32_e32 v50, v52
	v_mov_b32_e32 v51, v53
	s_or_b64 exec, exec, s[26:27]
	s_and_saveexec_b64 s[26:27], s[44:45]
	s_cbranch_execnz .LBB0_861

; DI unsigned pk2(float lo, float hi) { f32x2_t v; v[0] = lo; v[1] = hi; bf16x2_t b = __builtin_convertvector(v, bf16x2_t); return __builtin_bit_cast(unsigned, b); }
; DI float bflo(unsigned u) { return __uint_as_float(u << 16); }
; DI float bfhi(unsigned u) { return __uint_as_float(u & 0xffff0000u); }
; DI float siluf_(float x) { return x / (1.f + __expf(-x)); }
; DI void prep_ew_item(const Params& p, int l, int item, bf16_t* lds) {
;     ...
;       for (int i = 0; i < 4; ++i) {
;         const int ts = tl - 3 + i;
;         if (ts >= 0) {
;           u32x4 v = *(const u32x4*)(RC + (size_t)ts * 1536 + ch); unsigned w[4] = {v.x, v.y, v.z, v.w};
;           const float* cw = p.convw + ((size_t)l * 4 + i) * 1536 + ch;
;           f32x4 c0 = *(const f32x4*)cw, c1 = *(const f32x4*)(cw + 4);
;           a[0] += bflo(w[0]) * c0[0]; a[1] += bfhi(w[0]) * c0[1]; a[2] += bflo(w[1]) * c0[2]; a[3] += bfhi(w[1]) * c0[3];
;           a[4] += bflo(w[2]) * c1[0]; a[5] += bfhi(w[2]) * c1[1]; a[6] += bflo(w[3]) * c1[2]; a[7] += bfhi(w[3]) * c1[3];
;         }
;     ...
;       float ss = 0.f;
; #pragma unroll
;       for (int j = 0; j < 8; ++j) { a[j] = siluf_(a[j]); ss += a[j] * a[j]; }
;       float mul = 1.f;
;       if (part < 2) {
;         ss += __shfl_xor(ss, 1); ss += __shfl_xor(ss, 2); ss += __shfl_xor(ss, 4); ss += __shfl_xor(ss, 8);
;         mul = rsqrtf(ss + EPS) * (part == 0 ? 0.08838834764831845f : 1.f);
;       }
;       u32x4 o; o.x = pk2(a[0] * mul, a[1] * mul); o.y = pk2(a[2] * mul, a[3] * mul); o.z = pk2(a[4] * mul, a[5] * mul); o.w = pk2(a[6] * mul, a[7] * mul);
;       *(u32x4*)(CQ + (size_t)t * 1536 + ch) = o;
.LBB0_864:
	s_or_b64 exec, exec, s[26:27]
	v_mul_f32_e32 v54, 0xbfb8aa3b, v46
	v_exp_f32_e32 v64, v54
	v_mul_f32_e32 v54, 0xbfb8aa3b, v47
	v_exp_f32_e32 v65, v54
	v_mul_f32_e32 v54, 0xbfb8aa3b, v48
	v_exp_f32_e32 v66, v54
	v_mul_f32_e32 v54, 0xbfb8aa3b, v49
	v_exp_f32_e32 v67, v54
	v_mul_f32_e32 v54, 0xbfb8aa3b, v50
	v_mul_f32_e32 v55, 0xbfb8aa3b, v51
	v_exp_f32_e32 v54, v54
	v_exp_f32_e32 v55, v55
	v_pk_add_f32 v[66:67], v[66:67], 1.0 op_sel_hi:[1,0]
	v_pk_add_f32 v[64:65], v[64:65], 1.0 op_sel_hi:[1,0]
	v_mul_f32_e32 v52, 0xbfb8aa3b, v44
	v_pk_add_f32 v[54:55], v[54:55], 1.0 op_sel_hi:[1,0]
	v_mul_f32_e32 v53, 0xbfb8aa3b, v45
	v_div_scale_f32 v68, s[6:7], v55, v55, v51
	v_rcp_f32_e32 v69, v68
	v_exp_f32_e32 v52, v52
	v_exp_f32_e32 v53, v53
	v_fma_f32 v70, -v68, v69, 1.0
	v_fmac_f32_e32 v69, v70, v69
	v_div_scale_f32 v70, vcc, v51, v55, v51
	v_mul_f32_e32 v71, v70, v69
	v_fma_f32 v72, -v68, v71, v70
	v_fmac_f32_e32 v71, v72, v69
	v_fma_f32 v68, -v68, v71, v70
	v_div_fmas_f32 v68, v68, v69, v71
	v_div_fixup_f32 v51, v68, v55, v51
	v_div_scale_f32 v55, s[6:7], v54, v54, v50
	v_rcp_f32_e32 v68, v55
	v_pk_add_f32 v[52:53], v[52:53], 1.0 op_sel_hi:[1,0]
	v_fma_f32 v69, -v55, v68, 1.0
	v_fmac_f32_e32 v68, v69, v68
	v_div_scale_f32 v69, vcc, v50, v54, v50
	v_mul_f32_e32 v70, v69, v68
	v_fma_f32 v71, -v55, v70, v69
	v_fmac_f32_e32 v70, v71, v68
	v_fma_f32 v55, -v55, v70, v69
	v_div_fmas_f32 v55, v55, v68, v70
	v_div_scale_f32 v68, s[6:7], v67, v67, v49
	v_rcp_f32_e32 v69, v68
	v_div_fixup_f32 v50, v55, v54, v50
	v_pk_mul_f32 v[54:55], v[50:51], v[50:51]
	v_fma_f32 v70, -v68, v69, 1.0
	v_fmac_f32_e32 v69, v70, v69
	v_div_scale_f32 v70, vcc, v49, v67, v49
	v_mul_f32_e32 v71, v70, v69
	v_fma_f32 v72, -v68, v71, v70
	v_fmac_f32_e32 v71, v72, v69
	v_fma_f32 v68, -v68, v71, v70
	v_div_fmas_f32 v68, v68, v69, v71
	v_div_fixup_f32 v49, v68, v67, v49
	v_div_scale_f32 v67, s[6:7], v66, v66, v48
	v_rcp_f32_e32 v68, v67
	s_nop 0
	v_fma_f32 v69, -v67, v68, 1.0
	v_fmac_f32_e32 v68, v69, v68
	v_div_scale_f32 v69, vcc, v48, v66, v48
	v_mul_f32_e32 v70, v69, v68
	v_fma_f32 v71, -v67, v70, v69
	v_fmac_f32_e32 v70, v71, v68
	v_fma_f32 v67, -v67, v70, v69
	v_div_fmas_f32 v67, v67, v68, v70
	v_div_scale_f32 v68, s[6:7], v65, v65, v47
	v_rcp_f32_e32 v69, v68
	v_div_fixup_f32 v48, v67, v66, v48
	v_pk_mul_f32 v[66:67], v[48:49], v[48:49]
	v_fma_f32 v70, -v68, v69, 1.0
	v_fmac_f32_e32 v69, v70, v69
	v_div_scale_f32 v70, vcc, v47, v65, v47
	v_mul_f32_e32 v71, v70, v69
	v_fma_f32 v72, -v68, v71, v70
	v_fmac_f32_e32 v71, v72, v69
	v_fma_f32 v68, -v68, v71, v70
	v_div_fmas_f32 v68, v68, v69, v71
	v_div_fixup_f32 v47, v68, v65, v47
	v_div_scale_f32 v65, s[6:7], v64, v64, v46
	v_rcp_f32_e32 v68, v65
	s_nop 0
	v_fma_f32 v69, -v65, v68, 1.0
	v_fmac_f32_e32 v68, v69, v68
	v_div_scale_f32 v69, vcc, v46, v64, v46
	v_mul_f32_e32 v70, v69, v68
	v_fma_f32 v71, -v65, v70, v69
	v_fmac_f32_e32 v70, v71, v68
	v_fma_f32 v65, -v65, v70, v69
	v_div_fmas_f32 v65, v65, v68, v70
	v_div_scale_f32 v68, s[6:7], v53, v53, v45
	v_rcp_f32_e32 v69, v68
	v_div_fixup_f32 v46, v65, v64, v46
	v_pk_mul_f32 v[64:65], v[46:47], v[46:47]
	v_fma_f32 v70, -v68, v69, 1.0
	v_fmac_f32_e32 v69, v70, v69
	v_div_scale_f32 v70, vcc, v45, v53, v45
	v_mul_f32_e32 v71, v70, v69
	v_fma_f32 v72, -v68, v71, v70
	v_fmac_f32_e32 v71, v72, v69
	v_fma_f32 v68, -v68, v71, v70
	v_div_fmas_f32 v68, v68, v69, v71
	v_div_fixup_f32 v45, v68, v53, v45
	v_div_scale_f32 v53, s[6:7], v52, v52, v44
	v_rcp_f32_e32 v68, v53
	s_nop 0
	v_fma_f32 v69, -v53, v68, 1.0
	v_fmac_f32_e32 v68, v69, v68
	v_div_scale_f32 v69, vcc, v44, v52, v44
	v_mul_f32_e32 v70, v69, v68
	v_fma_f32 v71, -v53, v70, v69
	v_fmac_f32_e32 v70, v71, v68
	v_fma_f32 v53, -v53, v70, v69
	v_div_fmas_f32 v53, v53, v68, v70
	v_div_fixup_f32 v44, v53, v52, v44
	v_pk_mul_f32 v[52:53], v[44:45], v[44:45]
	s_nop 0
	v_add_f32_e32 v52, v52, v53
	v_add_f32_e32 v52, v64, v52
	v_add_f32_e32 v52, v65, v52
	v_add_f32_e32 v52, v66, v52
	v_add_f32_e32 v52, v67, v52
	v_add_f32_e32 v52, v54, v52
	v_add_f32_e32 v52, v55, v52
	s_nop 1
	v_add_f32_dpp v52, v52, v52 quad_perm:[1,0,3,2] row_mask:0xf bank_mask:0xf
	s_waitcnt lgkmcnt(0)
	s_nop 1
	v_add_f32_dpp v52, v52, v52 quad_perm:[2,3,0,1] row_mask:0xf bank_mask:0xf
	s_waitcnt lgkmcnt(0)
	s_nop 1
	v_add_f32_dpp v52, v52, v52 row_half_mirror row_mask:0xf bank_mask:0xf
	s_waitcnt lgkmcnt(0)
	s_nop 1
	v_add_f32_dpp v52, v52, v52 row_mirror row_mask:0xf bank_mask:0xf
	s_waitcnt lgkmcnt(0)
	v_add_f32_e32 v52, 0x358637bd, v52
	v_cmp_gt_f32_e32 vcc, s58, v52
	v_mul_f32_e32 v53, 0x4b800000, v52
	s_nop 0
	v_cndmask_b32_e32 v52, v52, v53, vcc
	v_rsq_f32_e32 v52, v52
	s_nop 0
	v_mul_f32_e32 v53, 0x45800000, v52
	v_cndmask_b32_e32 v52, v52, v53, vcc
	v_pk_mul_f32 v[44:45], v[44:45], v[52:53] op_sel_hi:[1,0]
	v_pk_mul_f32 v[46:47], v[46:47], v[52:53] op_sel_hi:[1,0]
	v_cvt_pk_bf16_f32 v44, v44, v45
	v_cvt_pk_bf16_f32 v45, v46, v47
	v_pk_mul_f32 v[46:47], v[48:49], v[52:53] op_sel_hi:[1,0]
	v_pk_mul_f32 v[48:49], v[50:51], v[52:53] op_sel_hi:[1,0]
	v_cvt_pk_bf16_f32 v46, v46, v47
	v_cvt_pk_bf16_f32 v47, v48, v49
	v_mov_b32_e32 v52, 0
	global_store_dwordx4 v[42:43], v[44:47], off offset:1024
	v_mov_b32_e32 v53, 0
	v_mov_b32_e32 v50, 0
	v_mov_b32_e32 v51, 0
	v_mov_b32_e32 v48, 0
	v_mov_b32_e32 v49, v52
	v_mov_b32_e32 v44, v52
	v_mov_b32_e32 v45, v52
	v_mov_b32_e32 v46, 0
	v_mov_b32_e32 v47, 0
	s_and_saveexec_b64 s[26:27], s[42:43]
	s_cbranch_execz .LBB0_868
	v_mad_u64_u32 v[44:45], s[6:7], v57, s57, v[38:39]
	global_load_dwordx4 v[44:47], v[44:45], off
	s_nop 0
	global_load_dwordx4 v[52:55], v[22:23], off offset:16
	global_load_dwordx4 v[64:67], v[22:23], off
	s_waitcnt vmcnt(2)
	v_lshlrev_b32_e32 v48, 16, v44
	v_and_b32_e32 v49, 0xffff0000, v44
	v_lshlrev_b32_e32 v44, 16, v45
	v_and_b32_e32 v45, 0xffff0000, v45
	s_waitcnt vmcnt(0)
	v_pk_fma_f32 v[50:51], v[64:65], v[48:49], 0 op_sel_hi:[1,1,0]
	v_pk_fma_f32 v[48:49], v[66:67], v[44:45], 0 op_sel_hi:[1,1,0]
	v_lshlrev_b32_e32 v44, 16, v46
	v_and_b32_e32 v45, 0xffff0000, v46
	v_lshlrev_b32_e32 v46, 16, v47
	v_and_b32_e32 v47, 0xffff0000, v47
	v_pk_fma_f32 v[44:45], v[52:53], v[44:45], 0 op_sel_hi:[1,1,0]
	v_pk_fma_f32 v[52:53], v[54:55], v[46:47], 0 op_sel_hi:[1,1,0]
	s_nop 0
	v_mov_b32_e32 v46, v52
	v_mov_b32_e32 v47, v53
	s_or_b64 exec, exec, s[26:27]
	s_and_saveexec_b64 s[26:27], s[44:45]
	s_cbranch_execnz .LBB0_869

; DI unsigned pk2(float lo, float hi) { f32x2_t v; v[0] = lo; v[1] = hi; bf16x2_t b = __builtin_convertvector(v, bf16x2_t); return __builtin_bit_cast(unsigned, b); }
; DI float bflo(unsigned u) { return __uint_as_float(u << 16); }
; DI float bfhi(unsigned u) { return __uint_as_float(u & 0xffff0000u); }
; DI float siluf_(float x) { return x / (1.f + __expf(-x)); }
; DI void prep_ew_item(const Params& p, int l, int item, bf16_t* lds) {
;     ...
;       for (int i = 0; i < 4; ++i) {
;         const int ts = tl - 3 + i;
;         if (ts >= 0) {
;           u32x4 v = *(const u32x4*)(RC + (size_t)ts * 1536 + ch); unsigned w[4] = {v.x, v.y, v.z, v.w};
;           const float* cw = p.convw + ((size_t)l * 4 + i) * 1536 + ch;
;           f32x4 c0 = *(const f32x4*)cw, c1 = *(const f32x4*)(cw + 4);
;           a[0] += bflo(w[0]) * c0[0]; a[1] += bfhi(w[0]) * c0[1]; a[2] += bflo(w[1]) * c0[2]; a[3] += bfhi(w[1]) * c0[3];
;           a[4] += bflo(w[2]) * c1[0]; a[5] += bfhi(w[2]) * c1[1]; a[6] += bflo(w[3]) * c1[2]; a[7] += bfhi(w[3]) * c1[3];
;         }
;     ...
;       float ss = 0.f;
; #pragma unroll
;       for (int j = 0; j < 8; ++j) { a[j] = siluf_(a[j]); ss += a[j] * a[j]; }
;       float mul = 1.f;
;       if (part < 2) {
;         ss += __shfl_xor(ss, 1); ss += __shfl_xor(ss, 2); ss += __shfl_xor(ss, 4); ss += __shfl_xor(ss, 8);
;         mul = rsqrtf(ss + EPS) * (part == 0 ? 0.08838834764831845f : 1.f);
;       }
;       u32x4 o; o.x = pk2(a[0] * mul, a[1] * mul); o.y = pk2(a[2] * mul, a[3] * mul); o.z = pk2(a[4] * mul, a[5] * mul); o.w = pk2(a[6] * mul, a[7] * mul);
;       *(u32x4*)(CQ + (size_t)t * 1536 + ch) = o;
.LBB0_886:
	s_or_b64 exec, exec, s[26:27]
	s_waitcnt vmcnt(1)
	v_mul_f32_e32 v41, 0xbfb8aa3b, v44
	v_exp_f32_e32 v52, v41
	v_mul_f32_e32 v41, 0xbfb8aa3b, v45
	v_exp_f32_e32 v53, v41
	v_mul_f32_e32 v41, 0xbfb8aa3b, v46
	v_exp_f32_e32 v56, v41
	v_mul_f32_e32 v41, 0xbfb8aa3b, v47
	v_exp_f32_e32 v57, v41
	v_mul_f32_e32 v41, 0xbfb8aa3b, v48
	v_exp_f32_e32 v64, v41
	v_mul_f32_e32 v41, 0xbfb8aa3b, v49
	v_exp_f32_e32 v65, v41
	v_mul_f32_e32 v41, 0xbfb8aa3b, v50
	v_exp_f32_e32 v54, v41
	v_mul_f32_e32 v41, 0xbfb8aa3b, v51
	v_exp_f32_e32 v55, v41
	v_pk_add_f32 v[64:65], v[64:65], 1.0 op_sel_hi:[1,0]
	v_pk_add_f32 v[56:57], v[56:57], 1.0 op_sel_hi:[1,0]
	v_pk_add_f32 v[52:53], v[52:53], 1.0 op_sel_hi:[1,0]
	v_pk_add_f32 v[54:55], v[54:55], 1.0 op_sel_hi:[1,0]
	s_nop 0
	v_div_scale_f32 v41, s[6:7], v55, v55, v51
	v_rcp_f32_e32 v66, v41
	s_nop 0
	v_fma_f32 v67, -v41, v66, 1.0
	v_fmac_f32_e32 v66, v67, v66
	v_div_scale_f32 v67, vcc, v51, v55, v51
	v_mul_f32_e32 v68, v67, v66
	v_fma_f32 v69, -v41, v68, v67
	v_fmac_f32_e32 v68, v69, v66
	v_fma_f32 v41, -v41, v68, v67
	v_div_fmas_f32 v41, v41, v66, v68
	v_div_fixup_f32 v51, v41, v55, v51
	v_div_scale_f32 v41, s[6:7], v54, v54, v50
	v_rcp_f32_e32 v55, v41
	s_nop 0
	v_fma_f32 v66, -v41, v55, 1.0
	v_fmac_f32_e32 v55, v66, v55
	v_div_scale_f32 v66, vcc, v50, v54, v50
	v_mul_f32_e32 v67, v66, v55
	v_fma_f32 v68, -v41, v67, v66
	v_fmac_f32_e32 v67, v68, v55
	v_fma_f32 v41, -v41, v67, v66
	v_div_fmas_f32 v41, v41, v55, v67
	v_div_fixup_f32 v50, v41, v54, v50
	v_div_scale_f32 v41, s[6:7], v65, v65, v49
	v_rcp_f32_e32 v66, v41
	v_pk_mul_f32 v[54:55], v[50:51], v[50:51]
	v_fma_f32 v67, -v41, v66, 1.0
	v_fmac_f32_e32 v66, v67, v66
	v_div_scale_f32 v67, vcc, v49, v65, v49
	v_mul_f32_e32 v68, v67, v66
	v_fma_f32 v69, -v41, v68, v67
	v_fmac_f32_e32 v68, v69, v66
	v_fma_f32 v41, -v41, v68, v67
	v_div_fmas_f32 v41, v41, v66, v68
	v_div_fixup_f32 v49, v41, v65, v49
	v_div_scale_f32 v41, s[6:7], v64, v64, v48
	v_rcp_f32_e32 v65, v41
	s_nop 0
	v_fma_f32 v66, -v41, v65, 1.0
	v_fmac_f32_e32 v65, v66, v65
	v_div_scale_f32 v66, vcc, v48, v64, v48
	v_mul_f32_e32 v67, v66, v65
	v_fma_f32 v68, -v41, v67, v66
	v_fmac_f32_e32 v67, v68, v65
	v_fma_f32 v41, -v41, v67, v66
	v_div_fmas_f32 v41, v41, v65, v67
	v_div_fixup_f32 v48, v41, v64, v48
	v_div_scale_f32 v41, s[6:7], v57, v57, v47
	v_rcp_f32_e32 v66, v41
	v_pk_mul_f32 v[64:65], v[48:49], v[48:49]
	v_fma_f32 v67, -v41, v66, 1.0
	v_fmac_f32_e32 v66, v67, v66
	v_div_scale_f32 v67, vcc, v47, v57, v47
	v_mul_f32_e32 v68, v67, v66
	v_fma_f32 v69, -v41, v68, v67
	v_fmac_f32_e32 v68, v69, v66
	v_fma_f32 v41, -v41, v68, v67
	v_div_fmas_f32 v41, v41, v66, v68
	v_div_fixup_f32 v57, v41, v57, v47
	v_div_scale_f32 v41, s[6:7], v56, v56, v46
	v_rcp_f32_e32 v47, v41
	s_nop 0
	v_fma_f32 v66, -v41, v47, 1.0
	v_fmac_f32_e32 v47, v66, v47
	v_div_scale_f32 v66, vcc, v46, v56, v46
	v_mul_f32_e32 v67, v66, v47
	v_fma_f32 v68, -v41, v67, v66
	v_fmac_f32_e32 v67, v68, v47
	v_fma_f32 v41, -v41, v67, v66
	v_div_fmas_f32 v41, v41, v47, v67
	v_div_fixup_f32 v56, v41, v56, v46
	v_div_scale_f32 v41, s[6:7], v53, v53, v45
	v_rcp_f32_e32 v66, v41
	v_pk_mul_f32 v[46:47], v[56:57], v[56:57]
	v_fma_f32 v67, -v41, v66, 1.0
	v_fmac_f32_e32 v66, v67, v66
	v_div_scale_f32 v67, vcc, v45, v53, v45
	v_mul_f32_e32 v68, v67, v66
	v_fma_f32 v69, -v41, v68, v67
	v_fmac_f32_e32 v68, v69, v66
	v_fma_f32 v41, -v41, v68, v67
	v_div_fmas_f32 v41, v41, v66, v68
	v_div_fixup_f32 v45, v41, v53, v45
	v_div_scale_f32 v41, s[6:7], v52, v52, v44
	v_rcp_f32_e32 v53, v41
	s_nop 0
	v_fma_f32 v66, -v41, v53, 1.0
	v_fmac_f32_e32 v53, v66, v53
	v_div_scale_f32 v66, vcc, v44, v52, v44
	v_mul_f32_e32 v67, v66, v53
	v_fma_f32 v68, -v41, v67, v66
	v_fmac_f32_e32 v67, v68, v53
	v_fma_f32 v41, -v41, v67, v66
	v_div_fmas_f32 v41, v41, v53, v67
	v_div_fixup_f32 v44, v41, v52, v44
	v_pk_mul_f32 v[52:53], v[44:45], v[44:45]
	s_nop 0
	v_add_f32_e32 v41, v52, v53
	v_add_f32_e32 v41, v46, v41
	v_add_f32_e32 v41, v47, v41
	v_add_f32_e32 v41, v64, v41
	v_add_f32_e32 v41, v65, v41
	v_add_f32_e32 v41, v54, v41
	v_add_f32_e32 v41, v55, v41
	s_nop 1
	v_add_f32_dpp v41, v41, v41 quad_perm:[1,0,3,2] row_mask:0xf bank_mask:0xf
	v_mov_b32_e32 v54, 0
	v_mov_b32_e32 v55, 0
	s_waitcnt lgkmcnt(0)
	s_nop 1
	v_add_f32_dpp v41, v41, v41 quad_perm:[2,3,0,1] row_mask:0xf bank_mask:0xf
	s_waitcnt lgkmcnt(0)
	s_nop 1
	v_add_f32_dpp v41, v41, v41 row_half_mirror row_mask:0xf bank_mask:0xf
	s_waitcnt lgkmcnt(0)
	s_nop 1
	v_add_f32_dpp v41, v41, v41 row_mirror row_mask:0xf bank_mask:0xf
	s_waitcnt lgkmcnt(0)
	v_add_f32_e32 v41, 0x358637bd, v41
	v_cmp_gt_f32_e32 vcc, s58, v41
	v_mul_f32_e32 v46, 0x4b800000, v41
	s_nop 0
	v_cndmask_b32_e32 v41, v41, v46, vcc
	v_rsq_f32_e32 v41, v41
	s_nop 0
	v_mul_f32_e32 v46, 0x45800000, v41
	v_cndmask_b32_e32 v41, v41, v46, vcc
	v_mul_f32_e32 v52, 0x3db504f3, v41
	v_pk_mul_f32 v[44:45], v[44:45], v[52:53] op_sel_hi:[1,0]
	s_nop 0
	v_cvt_pk_bf16_f32 v46, v44, v45
	v_pk_mul_f32 v[44:45], v[56:57], v[52:53] op_sel_hi:[1,0]
	s_nop 0
	v_cvt_pk_bf16_f32 v47, v44, v45
	v_pk_mul_f32 v[44:45], v[48:49], v[52:53] op_sel_hi:[1,0]
	s_nop 0
	v_cvt_pk_bf16_f32 v48, v44, v45
	v_pk_mul_f32 v[44:45], v[50:51], v[52:53] op_sel_hi:[1,0]
	v_mov_b32_e32 v50, v54
	v_cvt_pk_bf16_f32 v49, v44, v45
	v_mad_i64_i32 v[44:45], s[6:7], v42, s57, v[34:35]
	global_store_dwordx4 v[44:45], v[46:49], off
	v_mov_b32_e32 v51, v54
	v_mov_b32_e32 v52, 0
	v_mov_b32_e32 v46, 0
	v_mov_b32_e32 v47, 0
	v_mov_b32_e32 v48, 0
	v_mov_b32_e32 v49, v54
	v_mov_b32_e32 v53, 0
	s_and_saveexec_b64 s[26:27], s[42:43]
	s_cbranch_execz .LBB0_890
	v_mad_u64_u32 v[46:47], s[6:7], v62, s57, v[36:37]
	global_load_dwordx4 v[50:53], v[46:47], off
	global_load_dwordx4 v[54:57], v[8:9], off offset:2064
	s_nop 0
	global_load_dwordx4 v[46:49], v[8:9], off offset:2048
	s_waitcnt vmcnt(2)
	v_lshlrev_b32_e32 v64, 16, v50
	v_and_b32_e32 v65, 0xffff0000, v50
	v_lshlrev_b32_e32 v50, 16, v51
	v_and_b32_e32 v51, 0xffff0000, v51
	s_waitcnt vmcnt(0)
	v_pk_fma_f32 v[48:49], v[48:49], v[50:51], 0 op_sel_hi:[1,1,0]
	v_lshlrev_b32_e32 v50, 16, v52
	v_and_b32_e32 v51, 0xffff0000, v52
	v_lshlrev_b32_e32 v52, 16, v53
	v_and_b32_e32 v53, 0xffff0000, v53
	v_pk_fma_f32 v[50:51], v[54:55], v[50:51], 0 op_sel_hi:[1,1,0]
	v_pk_fma_f32 v[54:55], v[56:57], v[52:53], 0 op_sel_hi:[1,1,0]
	v_pk_fma_f32 v[46:47], v[46:47], v[64:65], 0 op_sel_hi:[1,1,0]
	v_mov_b32_e32 v52, v54
	v_mov_b32_e32 v53, v55
	s_or_b64 exec, exec, s[26:27]
	s_and_saveexec_b64 s[26:27], s[44:45]
	s_cbranch_execnz .LBB0_891

; DI unsigned pk2(float lo, float hi) { f32x2_t v; v[0] = lo; v[1] = hi; bf16x2_t b = __builtin_convertvector(v, bf16x2_t); return __builtin_bit_cast(unsigned, b); }
; DI float bflo(unsigned u) { return __uint_as_float(u << 16); }
; DI float bfhi(unsigned u) { return __uint_as_float(u & 0xffff0000u); }
; DI float siluf_(float x) { return x / (1.f + __expf(-x)); }
; DI void prep_ew_item(const Params& p, int l, int item, bf16_t* lds) {
;     ...
;       for (int i = 0; i < 4; ++i) {
;         const int ts = tl - 3 + i;
;         if (ts >= 0) {
;           u32x4 v = *(const u32x4*)(RC + (size_t)ts * 1536 + ch); unsigned w[4] = {v.x, v.y, v.z, v.w};
;           const float* cw = p.convw + ((size_t)l * 4 + i) * 1536 + ch;
;           f32x4 c0 = *(const f32x4*)cw, c1 = *(const f32x4*)(cw + 4);
;           a[0] += bflo(w[0]) * c0[0]; a[1] += bfhi(w[0]) * c0[1]; a[2] += bflo(w[1]) * c0[2]; a[3] += bfhi(w[1]) * c0[3];
;           a[4] += bflo(w[2]) * c1[0]; a[5] += bfhi(w[2]) * c1[1]; a[6] += bflo(w[3]) * c1[2]; a[7] += bfhi(w[3]) * c1[3];
;         }
;     ...
;       float ss = 0.f;
; #pragma unroll
;       for (int j = 0; j < 8; ++j) { a[j] = siluf_(a[j]); ss += a[j] * a[j]; }
;       float mul = 1.f;
;       if (part < 2) {
;         ss += __shfl_xor(ss, 1); ss += __shfl_xor(ss, 2); ss += __shfl_xor(ss, 4); ss += __shfl_xor(ss, 8);
;         mul = rsqrtf(ss + EPS) * (part == 0 ? 0.08838834764831845f : 1.f);
;       }
;       u32x4 o; o.x = pk2(a[0] * mul, a[1] * mul); o.y = pk2(a[2] * mul, a[3] * mul); o.z = pk2(a[4] * mul, a[5] * mul); o.w = pk2(a[6] * mul, a[7] * mul);
;       *(u32x4*)(CQ + (size_t)t * 1536 + ch) = o;
.LBB0_894:
	s_or_b64 exec, exec, s[26:27]
	v_mul_f32_e32 v41, 0xbfb8aa3b, v46
	v_exp_f32_e32 v54, v41
	v_mul_f32_e32 v41, 0xbfb8aa3b, v47
	v_exp_f32_e32 v55, v41
	v_mul_f32_e32 v41, 0xbfb8aa3b, v48
	v_exp_f32_e32 v64, v41
	v_mul_f32_e32 v41, 0xbfb8aa3b, v49
	v_exp_f32_e32 v65, v41
	v_mul_f32_e32 v41, 0xbfb8aa3b, v50
	v_exp_f32_e32 v66, v41
	v_mul_f32_e32 v41, 0xbfb8aa3b, v51
	v_exp_f32_e32 v67, v41
	v_mul_f32_e32 v41, 0xbfb8aa3b, v52
	v_exp_f32_e32 v56, v41
	v_mul_f32_e32 v41, 0xbfb8aa3b, v53
	v_exp_f32_e32 v57, v41
	v_pk_add_f32 v[66:67], v[66:67], 1.0 op_sel_hi:[1,0]
	v_pk_add_f32 v[64:65], v[64:65], 1.0 op_sel_hi:[1,0]
	v_pk_add_f32 v[54:55], v[54:55], 1.0 op_sel_hi:[1,0]
	v_pk_add_f32 v[56:57], v[56:57], 1.0 op_sel_hi:[1,0]
	s_nop 0
	v_div_scale_f32 v41, s[6:7], v57, v57, v53
	v_rcp_f32_e32 v68, v41
	s_nop 0
	v_fma_f32 v69, -v41, v68, 1.0
	v_fmac_f32_e32 v68, v69, v68
	v_div_scale_f32 v69, vcc, v53, v57, v53
	v_mul_f32_e32 v70, v69, v68
	v_fma_f32 v71, -v41, v70, v69
	v_fmac_f32_e32 v70, v71, v68
	v_fma_f32 v41, -v41, v70, v69
	v_div_fmas_f32 v41, v41, v68, v70
	v_div_fixup_f32 v53, v41, v57, v53
	v_div_scale_f32 v41, s[6:7], v56, v56, v52
	v_rcp_f32_e32 v57, v41
	s_nop 0
	v_fma_f32 v68, -v41, v57, 1.0
	v_fmac_f32_e32 v57, v68, v57
	v_div_scale_f32 v68, vcc, v52, v56, v52
	v_mul_f32_e32 v69, v68, v57
	v_fma_f32 v70, -v41, v69, v68
	v_fmac_f32_e32 v69, v70, v57
	v_fma_f32 v41, -v41, v69, v68
	v_div_fmas_f32 v41, v41, v57, v69
	v_div_fixup_f32 v52, v41, v56, v52
	v_div_scale_f32 v41, s[6:7], v67, v67, v51
	v_rcp_f32_e32 v68, v41
	v_pk_mul_f32 v[56:57], v[52:53], v[52:53]
	v_fma_f32 v69, -v41, v68, 1.0
	v_fmac_f32_e32 v68, v69, v68
	v_div_scale_f32 v69, vcc, v51, v67, v51
	v_mul_f32_e32 v70, v69, v68
	v_fma_f32 v71, -v41, v70, v69
	v_fmac_f32_e32 v70, v71, v68
	v_fma_f32 v41, -v41, v70, v69
	v_div_fmas_f32 v41, v41, v68, v70
	v_div_fixup_f32 v51, v41, v67, v51
	v_div_scale_f32 v41, s[6:7], v66, v66, v50
	v_rcp_f32_e32 v67, v41
	s_nop 0
	v_fma_f32 v68, -v41, v67, 1.0
	v_fmac_f32_e32 v67, v68, v67
	v_div_scale_f32 v68, vcc, v50, v66, v50
	v_mul_f32_e32 v69, v68, v67
	v_fma_f32 v70, -v41, v69, v68
	v_fmac_f32_e32 v69, v70, v67
	v_fma_f32 v41, -v41, v69, v68
	v_div_fmas_f32 v41, v41, v67, v69
	v_div_fixup_f32 v50, v41, v66, v50
	v_div_scale_f32 v41, s[6:7], v65, v65, v49
	v_rcp_f32_e32 v68, v41
	v_pk_mul_f32 v[66:67], v[50:51], v[50:51]
	v_fma_f32 v69, -v41, v68, 1.0
	v_fmac_f32_e32 v68, v69, v68
	v_div_scale_f32 v69, vcc, v49, v65, v49
	v_mul_f32_e32 v70, v69, v68
	v_fma_f32 v71, -v41, v70, v69
	v_fmac_f32_e32 v70, v71, v68
	v_fma_f32 v41, -v41, v70, v69
	v_div_fmas_f32 v41, v41, v68, v70
	v_div_fixup_f32 v49, v41, v65, v49
	v_div_scale_f32 v41, s[6:7], v64, v64, v48
	v_rcp_f32_e32 v65, v41
	s_nop 0
	v_fma_f32 v68, -v41, v65, 1.0
	v_fmac_f32_e32 v65, v68, v65
	v_div_scale_f32 v68, vcc, v48, v64, v48
	v_mul_f32_e32 v69, v68, v65
	v_fma_f32 v70, -v41, v69, v68
	v_fmac_f32_e32 v69, v70, v65
	v_fma_f32 v41, -v41, v69, v68
	v_div_fmas_f32 v41, v41, v65, v69
	v_div_fixup_f32 v48, v41, v64, v48
	v_div_scale_f32 v41, s[6:7], v55, v55, v47
	v_rcp_f32_e32 v68, v41
	v_pk_mul_f32 v[64:65], v[48:49], v[48:49]
	v_fma_f32 v69, -v41, v68, 1.0
	v_fmac_f32_e32 v68, v69, v68
	v_div_scale_f32 v69, vcc, v47, v55, v47
	v_mul_f32_e32 v70, v69, v68
	v_fma_f32 v71, -v41, v70, v69
	v_fmac_f32_e32 v70, v71, v68
	v_fma_f32 v41, -v41, v70, v69
	v_div_fmas_f32 v41, v41, v68, v70
	v_div_fixup_f32 v47, v41, v55, v47
	v_div_scale_f32 v41, s[6:7], v54, v54, v46
	v_rcp_f32_e32 v55, v41
	s_nop 0
	v_fma_f32 v68, -v41, v55, 1.0
	v_fmac_f32_e32 v55, v68, v55
	v_div_scale_f32 v68, vcc, v46, v54, v46
	v_mul_f32_e32 v69, v68, v55
	v_fma_f32 v70, -v41, v69, v68
	v_fmac_f32_e32 v69, v70, v55
	v_fma_f32 v41, -v41, v69, v68
	v_div_fmas_f32 v41, v41, v55, v69
	v_div_fixup_f32 v46, v41, v54, v46
	v_pk_mul_f32 v[54:55], v[46:47], v[46:47]
	s_nop 0
	v_add_f32_e32 v41, v54, v55
	v_add_f32_e32 v41, v64, v41
	v_add_f32_e32 v41, v65, v41
	v_add_f32_e32 v41, v66, v41
	v_add_f32_e32 v41, v67, v41
	v_add_f32_e32 v41, v56, v41
	v_add_f32_e32 v41, v57, v41
	s_nop 1
	v_add_f32_dpp v41, v41, v41 quad_perm:[1,0,3,2] row_mask:0xf bank_mask:0xf
	s_waitcnt lgkmcnt(0)
	s_nop 1
	v_add_f32_dpp v41, v41, v41 quad_perm:[2,3,0,1] row_mask:0xf bank_mask:0xf
	s_waitcnt lgkmcnt(0)
	s_nop 1
	v_add_f32_dpp v41, v41, v41 row_half_mirror row_mask:0xf bank_mask:0xf
	s_waitcnt lgkmcnt(0)
	s_nop 1
	v_add_f32_dpp v41, v41, v41 row_mirror row_mask:0xf bank_mask:0xf
	s_waitcnt lgkmcnt(0)
	v_add_f32_e32 v41, 0x358637bd, v41
	v_cmp_gt_f32_e32 vcc, s58, v41
	v_mul_f32_e32 v54, 0x4b800000, v41
	s_nop 0
	v_cndmask_b32_e32 v41, v41, v54, vcc
	v_rsq_f32_e32 v41, v41
	s_nop 0
	v_mul_f32_e32 v54, 0x45800000, v41
	v_cndmask_b32_e32 v54, v41, v54, vcc
	v_pk_mul_f32 v[46:47], v[46:47], v[54:55] op_sel_hi:[1,0]
	v_pk_mul_f32 v[48:49], v[48:49], v[54:55] op_sel_hi:[1,0]
	v_cvt_pk_bf16_f32 v46, v46, v47
	v_cvt_pk_bf16_f32 v47, v48, v49
	v_pk_mul_f32 v[48:49], v[50:51], v[54:55] op_sel_hi:[1,0]
	v_pk_mul_f32 v[50:51], v[52:53], v[54:55] op_sel_hi:[1,0]
	v_cvt_pk_bf16_f32 v48, v48, v49
	v_cvt_pk_bf16_f32 v49, v50, v51
	v_mov_b32_e32 v54, 0
	global_store_dwordx4 v[44:45], v[46:49], off offset:1024
	v_mov_b32_e32 v55, 0
	v_mov_b32_e32 v52, 0
	v_mov_b32_e32 v53, 0
	v_mov_b32_e32 v50, 0
	v_mov_b32_e32 v51, v54
	v_mov_b32_e32 v46, v54
	v_mov_b32_e32 v47, v54
	v_mov_b32_e32 v48, 0
	v_mov_b32_e32 v49, 0
	s_and_saveexec_b64 s[26:27], s[42:43]
	s_cbranch_execz .LBB0_898
	v_mad_u64_u32 v[46:47], s[6:7], v62, s57, v[38:39]
	global_load_dwordx4 v[46:49], v[46:47], off
	s_nop 0
	global_load_dwordx4 v[54:57], v[22:23], off offset:16
	global_load_dwordx4 v[64:67], v[22:23], off
	s_waitcnt vmcnt(2)
	v_lshlrev_b32_e32 v50, 16, v46
	v_and_b32_e32 v51, 0xffff0000, v46
	v_lshlrev_b32_e32 v46, 16, v47
	v_and_b32_e32 v47, 0xffff0000, v47
	s_waitcnt vmcnt(0)
	v_pk_fma_f32 v[52:53], v[64:65], v[50:51], 0 op_sel_hi:[1,1,0]
	v_pk_fma_f32 v[50:51], v[66:67], v[46:47], 0 op_sel_hi:[1,1,0]
	v_lshlrev_b32_e32 v46, 16, v48
	v_and_b32_e32 v47, 0xffff0000, v48
	v_lshlrev_b32_e32 v48, 16, v49
	v_and_b32_e32 v49, 0xffff0000, v49
	v_pk_fma_f32 v[46:47], v[54:55], v[46:47], 0 op_sel_hi:[1,1,0]
	v_pk_fma_f32 v[54:55], v[56:57], v[48:49], 0 op_sel_hi:[1,1,0]
	s_nop 0
	v_mov_b32_e32 v48, v54
	v_mov_b32_e32 v49, v55
	s_or_b64 exec, exec, s[26:27]
	s_and_saveexec_b64 s[26:27], s[44:45]
	s_cbranch_execnz .LBB0_899

; DI void mod_item(const Params& p, int item, float* red) {
;     ...
;   for (int k = kq * 256; k < kq * 256 + 256; ++k) { float wv = w[(size_t)k * 6144 + col]; a0 += p.c[k] * wv; a1 += p.c[1024 + k] * wv; }
;   __syncthreads();
;   red[(kq * 64 + (tid & 63)) * 2] = a0; red[(kq * 64 + (tid & 63)) * 2 + 1] = a1;
;   __syncthreads();
;   if (tid < 128) {
;     int cc = tid & 63, b = tid >> 6; float s = 0.f;
;     for (int q = 0; q < 4; ++q) s += red[(q * 64 + cc) * 2 + b];
;     float* mod = (float*)(p.ws + OFF_MOD);
;     mod[(l * 2 + b) * 6144 + n0 + cc] = s + p.ada_b[l * 6144 + n0 + cc];
.LBB0_1002:
	v_lshl_add_u64 v[16:17], v[4:5], 0, s[20:21]
	global_load_dwordx4 v[72:75], v[16:17], off
	global_load_dwordx4 v[76:79], v[16:17], off offset:16
	global_load_dwordx4 v[80:83], v[16:17], off offset:32
	global_load_dwordx4 v[84:87], v[16:17], off offset:48
	v_add_co_u32_e32 v16, vcc, s59, v16
	s_nop 1
	v_addc_co_u32_e32 v17, vcc, 0, v17, vcc
	global_load_dwordx4 v[88:91], v[16:17], off
	global_load_dwordx4 v[92:95], v[16:17], off offset:16
	global_load_dwordx4 v[96:99], v[16:17], off offset:32
	global_load_dwordx4 v[100:103], v[16:17], off offset:48
	v_add_co_u32_e32 v12, vcc, 0xfffee000, v2
	s_nop 1
	v_addc_co_u32_e32 v13, vcc, -1, v3, vcc
	s_mov_b64 s[8:9], 0x6000
	global_load_dword v56, v[12:13], off
	v_lshl_add_u64 v[12:13], v[12:13], 0, s[8:9]
	global_load_dword v57, v[12:13], off
	v_lshl_add_u64 v[12:13], v[12:13], 0, s[8:9]
	global_load_dword v58, v[12:13], off
	v_lshl_add_u64 v[12:13], v[12:13], 0, s[8:9]
	global_load_dword v59, v[12:13], off
	v_lshl_add_u64 v[12:13], v[12:13], 0, s[8:9]
	global_load_dword v60, v[12:13], off
	v_lshl_add_u64 v[12:13], v[12:13], 0, s[8:9]
	global_load_dword v61, v[12:13], off
	v_lshl_add_u64 v[12:13], v[12:13], 0, s[8:9]
	global_load_dword v62, v[12:13], off
	v_lshl_add_u64 v[12:13], v[12:13], 0, s[8:9]
	global_load_dword v63, v[12:13], off
	v_lshl_add_u64 v[12:13], v[12:13], 0, s[8:9]
	global_load_dword v64, v[12:13], off
	v_lshl_add_u64 v[12:13], v[12:13], 0, s[8:9]
	global_load_dword v65, v[12:13], off
	v_lshl_add_u64 v[12:13], v[12:13], 0, s[8:9]
	global_load_dword v66, v[12:13], off
	v_lshl_add_u64 v[12:13], v[12:13], 0, s[8:9]
	global_load_dword v67, v[12:13], off
	v_lshl_add_u64 v[12:13], v[12:13], 0, s[8:9]
	global_load_dword v68, v[12:13], off
	v_lshl_add_u64 v[12:13], v[12:13], 0, s[8:9]
	global_load_dword v69, v[12:13], off
	v_lshl_add_u64 v[12:13], v[12:13], 0, s[8:9]
	global_load_dword v70, v[12:13], off
	v_lshl_add_u64 v[12:13], v[12:13], 0, s[8:9]
	global_load_dword v71, v[12:13], off
	s_add_u32 s20, s20, 64
	s_addc_u32 s21, s21, 0
	s_mov_b64 s[8:9], 0x60000
	v_lshl_add_u64 v[2:3], v[2:3], 0, s[8:9]
	s_waitcnt vmcnt(0)
	v_mov_b32_e32 v0, v56
	v_mov_b32_e32 v20, v72
	v_mov_b32_e32 v21, v88
	v_pk_fma_f32 v[6:7], v[0:1], v[20:21], v[6:7] op_sel_hi:[0,1,1]
	v_mov_b32_e32 v0, v57
	v_mov_b32_e32 v20, v73
	v_mov_b32_e32 v21, v89
	v_pk_fma_f32 v[6:7], v[0:1], v[20:21], v[6:7] op_sel_hi:[0,1,1]
	v_mov_b32_e32 v0, v58
	v_mov_b32_e32 v20, v74
	v_mov_b32_e32 v21, v90
	v_pk_fma_f32 v[6:7], v[0:1], v[20:21], v[6:7] op_sel_hi:[0,1,1]
	v_mov_b32_e32 v0, v59
	v_mov_b32_e32 v20, v75
	v_mov_b32_e32 v21, v91
	v_pk_fma_f32 v[6:7], v[0:1], v[20:21], v[6:7] op_sel_hi:[0,1,1]
	v_mov_b32_e32 v0, v60
	v_mov_b32_e32 v20, v76
	v_mov_b32_e32 v21, v92
	v_pk_fma_f32 v[6:7], v[0:1], v[20:21], v[6:7] op_sel_hi:[0,1,1]
	v_mov_b32_e32 v0, v61
	v_mov_b32_e32 v20, v77
	v_mov_b32_e32 v21, v93
	v_pk_fma_f32 v[6:7], v[0:1], v[20:21], v[6:7] op_sel_hi:[0,1,1]
	v_mov_b32_e32 v0, v62
	v_mov_b32_e32 v20, v78
	v_mov_b32_e32 v21, v94
	v_pk_fma_f32 v[6:7], v[0:1], v[20:21], v[6:7] op_sel_hi:[0,1,1]
	v_mov_b32_e32 v0, v63
	v_mov_b32_e32 v20, v79
	v_mov_b32_e32 v21, v95
	v_pk_fma_f32 v[6:7], v[0:1], v[20:21], v[6:7] op_sel_hi:[0,1,1]
	v_mov_b32_e32 v0, v64
	v_mov_b32_e32 v20, v80
	v_mov_b32_e32 v21, v96
	v_pk_fma_f32 v[6:7], v[0:1], v[20:21], v[6:7] op_sel_hi:[0,1,1]
	v_mov_b32_e32 v0, v65
	v_mov_b32_e32 v20, v81
	v_mov_b32_e32 v21, v97
	v_pk_fma_f32 v[6:7], v[0:1], v[20:21], v[6:7] op_sel_hi:[0,1,1]
	v_mov_b32_e32 v0, v66
	v_mov_b32_e32 v20, v82
	v_mov_b32_e32 v21, v98
	v_pk_fma_f32 v[6:7], v[0:1], v[20:21], v[6:7] op_sel_hi:[0,1,1]
	v_mov_b32_e32 v0, v67
	v_mov_b32_e32 v20, v83
	v_mov_b32_e32 v21, v99
	v_pk_fma_f32 v[6:7], v[0:1], v[20:21], v[6:7] op_sel_hi:[0,1,1]
	v_mov_b32_e32 v0, v68
	v_mov_b32_e32 v20, v84
	v_mov_b32_e32 v21, v100
	v_pk_fma_f32 v[6:7], v[0:1], v[20:21], v[6:7] op_sel_hi:[0,1,1]
	v_mov_b32_e32 v0, v69
	v_mov_b32_e32 v20, v85
	v_mov_b32_e32 v21, v101
	v_pk_fma_f32 v[6:7], v[0:1], v[20:21], v[6:7] op_sel_hi:[0,1,1]
	v_mov_b32_e32 v0, v70
	v_mov_b32_e32 v20, v86
	v_mov_b32_e32 v21, v102
	v_pk_fma_f32 v[6:7], v[0:1], v[20:21], v[6:7] op_sel_hi:[0,1,1]
	v_mov_b32_e32 v0, v71
	v_mov_b32_e32 v20, v87
	v_mov_b32_e32 v21, v103
	v_pk_fma_f32 v[6:7], v[0:1], v[20:21], v[6:7] op_sel_hi:[0,1,1]
	s_cmpk_eq_i32 s20, 0x400
	s_cbranch_scc0 .LBB0_1002
	s_movk_i32 s8, 0x80
	v_lshlrev_b32_e32 v0, 3, v10
	v_cmp_gt_i32_e32 vcc, s8, v10
	s_barrier
	ds_write_b64 v0, v[6:7]
	s_waitcnt lgkmcnt(0)
	s_barrier
	s_and_saveexec_b64 s[20:21], vcc
	s_cbranch_execz .LBB0_1005
	v_lshlrev_b32_e32 v0, 2, v9
	v_lshl_add_u32 v0, v8, 3, v0
	ds_read2st64_b32 v[2:3], v0 offset1:2
	s_and_b64 s[8:9], s[0:1], exec
	s_cselect_b32 s8, 0x1800, 0
	s_add_i32 s8, s7, s8
	v_readlane_b32 s68, v253, 60
	s_waitcnt lgkmcnt(0)
	v_add_f32_e32 v2, 0, v2
	v_add_f32_e32 v4, v2, v3
	ds_read2st64_b32 v[2:3], v0 offset0:4 offset1:6
	v_readlane_b32 s76, v254, 4
	v_readlane_b32 s77, v254, 5
	s_and_b64 s[0:1], s[0:1], exec
	s_cselect_b32 s0, 2, 0
	s_waitcnt lgkmcnt(0)
	v_add_f32_e32 v0, v4, v2
	v_add_f32_e32 v4, v0, v3
	v_or_b32_e32 v0, s8, v8
	v_lshl_add_u64 v[2:3], v[0:1], 2, s[76:77]
	global_load_dword v0, v[2:3], off
	v_add_u32_e32 v2, s0, v9
	s_movk_i32 s0, 0x1800
	v_mul_lo_u32 v2, v2, s0
	v_add_u32_e32 v2, s7, v2
	v_readlane_b32 s69, v253, 61
	v_readlane_b32 s70, v253, 62
	v_readlane_b32 s71, v253, 63
	v_readlane_b32 s72, v254, 0
	v_readlane_b32 s73, v254, 1
	v_readlane_b32 s74, v254, 2
	v_readlane_b32 s75, v254, 3
	v_or_b32_e32 v2, v2, v8
	v_readlane_b32 s60, v254, 16
	v_ashrrev_i32_e32 v3, 31, v2
	v_readlane_b32 s61, v254, 17
	v_readlane_b32 s62, v254, 18
	v_readlane_b32 s63, v254, 19
	v_readlane_b32 s64, v254, 20
	v_readlane_b32 s65, v254, 21
	v_readlane_b32 s66, v254, 22
	v_readlane_b32 s67, v254, 23
	v_readlane_b32 s68, v254, 24
	v_readlane_b32 s69, v254, 25
	v_readlane_b32 s70, v254, 26
	v_readlane_b32 s71, v254, 27
	v_readlane_b32 s72, v254, 28
	v_readlane_b32 s73, v254, 29
	v_readlane_b32 s74, v254, 30
	v_readlane_b32 s75, v254, 31
	v_readlane_b32 s76, v254, 45
	v_lshl_add_u64 v[2:3], v[2:3], 2, s[2:3]
	v_readlane_b32 s78, v254, 6
	v_readlane_b32 s79, v254, 7
	v_readlane_b32 s80, v254, 8
	v_readlane_b32 s81, v254, 9
	v_readlane_b32 s82, v254, 10
	v_readlane_b32 s83, v254, 11
	s_waitcnt vmcnt(0)
	v_add_f32_e32 v0, v4, v0
	global_store_dword v[2:3], v0, off
